# adds FF1 epilogue rewrite: batched ssq loads, rstd via v_rsq_f32+Newton (f32), pk_mul scale/square
# baseline (speedup 1.0000x reference)
.LBB0_1961:
	v_lshl_add_u32 v142, s40, 8, v146
	v_lshl_or_b32 v143, s10, 8, v148
	v_readfirstlane_b32 s10, v136
	v_readfirstlane_b32 s11, v137
	v_xor_b32_e32 v145, 16, v1
	v_xor_b32_e32 v176, 32, v1
	v_lshlrev_b32_e32 v145, 2, v145
	v_lshlrev_b32_e32 v176, 2, v176
	v_subrev_u32_e32 v144, s10, v136
	v_lshl_add_u32 v144, v142, 7, v144
	s_add_u32 s40, s10, 0x0
	s_addc_u32 s41, s11, 0
	global_load_dwordx4 v[150:153], v144, s[40:41]
	global_load_dwordx4 v[154:157], v144, s[40:41] offset:16
	s_add_u32 s40, s10, 0x800
	s_addc_u32 s41, s11, 0
	global_load_dwordx4 v[158:161], v144, s[40:41]
	global_load_dwordx4 v[168:171], v144, s[40:41] offset:16
	s_add_u32 s40, s10, 0x1000
	s_addc_u32 s41, s11, 0
	global_load_dwordx4 v[172:175], v144, s[40:41]
	global_load_dwordx4 v[180:183], v144, s[40:41] offset:16
	s_add_u32 s40, s10, 0x1800
	s_addc_u32 s41, s11, 0
	global_load_dwordx4 v[184:187], v144, s[40:41]
	global_load_dwordx4 v[188:191], v144, s[40:41] offset:16
	s_add_u32 s40, s10, 0x4000
	s_addc_u32 s41, s11, 0
	global_load_dwordx4 v[192:195], v144, s[40:41]
	global_load_dwordx4 v[196:199], v144, s[40:41] offset:16
	s_add_u32 s40, s10, 0x4800
	s_addc_u32 s41, s11, 0
	global_load_dwordx4 v[200:203], v144, s[40:41]
	global_load_dwordx4 v[204:207], v144, s[40:41] offset:16
	s_add_u32 s40, s10, 0x5000
	s_addc_u32 s41, s11, 0
	global_load_dwordx4 v[214:217], v144, s[40:41]
	global_load_dwordx4 v[230:233], v144, s[40:41] offset:16
	s_add_u32 s40, s10, 0x5800
	s_addc_u32 s41, s11, 0
	global_load_dwordx4 v[234:237], v144, s[40:41]
	global_load_dwordx4 v[238:241], v144, s[40:41] offset:16
	s_waitcnt vmcnt(14)
	v_add_f32_e32 v150, v150, v151
	v_add_f32_e32 v152, v152, v153
	v_add_f32_e32 v154, v154, v155
	v_add_f32_e32 v156, v156, v157
	v_add_f32_e32 v150, v150, v152
	v_add_f32_e32 v154, v154, v156
	v_add_f32_e32 v150, v150, v154
	s_waitcnt vmcnt(12)
	v_add_f32_e32 v158, v158, v159
	v_add_f32_e32 v160, v160, v161
	v_add_f32_e32 v168, v168, v169
	v_add_f32_e32 v170, v170, v171
	v_add_f32_e32 v158, v158, v160
	v_add_f32_e32 v168, v168, v170
	v_add_f32_e32 v158, v158, v168
	s_waitcnt vmcnt(10)
	v_add_f32_e32 v172, v172, v173
	v_add_f32_e32 v174, v174, v175
	v_add_f32_e32 v180, v180, v181
	v_add_f32_e32 v182, v182, v183
	v_add_f32_e32 v172, v172, v174
	v_add_f32_e32 v180, v180, v182
	v_add_f32_e32 v172, v172, v180
	s_waitcnt vmcnt(8)
	v_add_f32_e32 v184, v184, v185
	v_add_f32_e32 v186, v186, v187
	v_add_f32_e32 v188, v188, v189
	v_add_f32_e32 v190, v190, v191
	v_add_f32_e32 v184, v184, v186
	v_add_f32_e32 v188, v188, v190
	v_add_f32_e32 v184, v184, v188
	s_waitcnt vmcnt(6)
	v_add_f32_e32 v192, v192, v193
	v_add_f32_e32 v194, v194, v195
	v_add_f32_e32 v196, v196, v197
	v_add_f32_e32 v198, v198, v199
	v_add_f32_e32 v192, v192, v194
	v_add_f32_e32 v196, v196, v198
	v_add_f32_e32 v192, v192, v196
	s_waitcnt vmcnt(4)
	v_add_f32_e32 v200, v200, v201
	v_add_f32_e32 v202, v202, v203
	v_add_f32_e32 v204, v204, v205
	v_add_f32_e32 v206, v206, v207
	v_add_f32_e32 v200, v200, v202
	v_add_f32_e32 v204, v204, v206
	v_add_f32_e32 v200, v200, v204
	s_waitcnt vmcnt(2)
	v_add_f32_e32 v214, v214, v215
	v_add_f32_e32 v216, v216, v217
	v_add_f32_e32 v230, v230, v231
	v_add_f32_e32 v232, v232, v233
	v_add_f32_e32 v214, v214, v216
	v_add_f32_e32 v230, v230, v232
	v_add_f32_e32 v214, v214, v230
	s_waitcnt vmcnt(0)
	v_add_f32_e32 v234, v234, v235
	v_add_f32_e32 v236, v236, v237
	v_add_f32_e32 v238, v238, v239
	v_add_f32_e32 v240, v240, v241
	v_add_f32_e32 v234, v234, v236
	v_add_f32_e32 v238, v238, v240
	v_add_f32_e32 v234, v234, v238
	ds_bpermute_b32 v154, v145, v150
	ds_bpermute_b32 v168, v145, v158
	ds_bpermute_b32 v180, v145, v172
	ds_bpermute_b32 v188, v145, v184
	ds_bpermute_b32 v196, v145, v192
	ds_bpermute_b32 v204, v145, v200
	ds_bpermute_b32 v230, v145, v214
	ds_bpermute_b32 v238, v145, v234
	s_waitcnt lgkmcnt(7)
	v_add_f32_e32 v150, v150, v154
	s_waitcnt lgkmcnt(6)
	v_add_f32_e32 v158, v158, v168
	s_waitcnt lgkmcnt(5)
	v_add_f32_e32 v172, v172, v180
	s_waitcnt lgkmcnt(4)
	v_add_f32_e32 v184, v184, v188
	s_waitcnt lgkmcnt(3)
	v_add_f32_e32 v192, v192, v196
	s_waitcnt lgkmcnt(2)
	v_add_f32_e32 v200, v200, v204
	s_waitcnt lgkmcnt(1)
	v_add_f32_e32 v214, v214, v230
	s_waitcnt lgkmcnt(0)
	v_add_f32_e32 v234, v234, v238
	ds_bpermute_b32 v154, v176, v150
	ds_bpermute_b32 v168, v176, v158
	ds_bpermute_b32 v180, v176, v172
	ds_bpermute_b32 v188, v176, v184
	ds_bpermute_b32 v196, v176, v192
	ds_bpermute_b32 v204, v176, v200
	ds_bpermute_b32 v230, v176, v214
	ds_bpermute_b32 v238, v176, v234
	s_waitcnt lgkmcnt(7)
	v_add_f32_e32 v150, v150, v154
	s_waitcnt lgkmcnt(6)
	v_add_f32_e32 v158, v158, v168
	s_waitcnt lgkmcnt(5)
	v_add_f32_e32 v172, v172, v180
	s_waitcnt lgkmcnt(4)
	v_add_f32_e32 v184, v184, v188
	s_waitcnt lgkmcnt(3)
	v_add_f32_e32 v192, v192, v196
	s_waitcnt lgkmcnt(2)
	v_add_f32_e32 v200, v200, v204
	s_waitcnt lgkmcnt(1)
	v_add_f32_e32 v214, v214, v230
	s_waitcnt lgkmcnt(0)
	v_add_f32_e32 v234, v234, v238
	v_mov_b32_e32 v177, 0x3a000000
	v_fma_f32 v150, v150, v177, v226
	v_fma_f32 v158, v158, v177, v226
	v_fma_f32 v172, v172, v177, v226
	v_fma_f32 v184, v184, v177, v226
	v_fma_f32 v192, v192, v177, v226
	v_fma_f32 v200, v200, v177, v226
	v_fma_f32 v214, v214, v177, v226
	v_fma_f32 v234, v234, v177, v226
	v_rsq_f32_e32 v151, v150
	v_rsq_f32_e32 v159, v158
	v_rsq_f32_e32 v173, v172
	v_rsq_f32_e32 v185, v184
	v_rsq_f32_e32 v193, v192
	v_rsq_f32_e32 v201, v200
	v_rsq_f32_e32 v215, v214
	v_rsq_f32_e32 v235, v234
	v_mul_f32_e32 v152, v150, v151
	v_mul_f32_e32 v160, v158, v159
	v_mul_f32_e32 v174, v172, v173
	v_mul_f32_e32 v186, v184, v185
	v_mul_f32_e32 v194, v192, v193
	v_mul_f32_e32 v202, v200, v201
	v_mul_f32_e32 v216, v214, v215
	v_mul_f32_e32 v236, v234, v235
	v_mul_f32_e32 v153, 0.5, v151
	v_mul_f32_e32 v161, 0.5, v159
	v_mul_f32_e32 v175, 0.5, v173
	v_mul_f32_e32 v187, 0.5, v185
	v_mul_f32_e32 v195, 0.5, v193
	v_mul_f32_e32 v203, 0.5, v201
	v_mul_f32_e32 v217, 0.5, v215
	v_mul_f32_e32 v237, 0.5, v235
	v_fma_f32 v152, -v152, v153, 0.5
	v_fma_f32 v160, -v160, v161, 0.5
	v_fma_f32 v174, -v174, v175, 0.5
	v_fma_f32 v186, -v186, v187, 0.5
	v_fma_f32 v194, -v194, v195, 0.5
	v_fma_f32 v202, -v202, v203, 0.5
	v_fma_f32 v216, -v216, v217, 0.5
	v_fma_f32 v236, -v236, v237, 0.5
	v_fma_f32 v150, v151, v152, v151
	v_fma_f32 v158, v159, v160, v159
	v_fma_f32 v172, v173, v174, v173
	v_fma_f32 v184, v185, v186, v185
	v_fma_f32 v192, v193, v194, v193
	v_fma_f32 v200, v201, v202, v201
	v_fma_f32 v214, v215, v216, v215
	v_fma_f32 v234, v235, v236, v235
	v_lshlrev_b32_e32 v178, 14, v142
	v_lshl_add_u32 v178, v143, 1, v178
	s_add_u32 s40, s22, 0x0
	s_addc_u32 s41, s23, 0
	v_pk_mul_f32 v[126:127], v[126:127], v[150:151] op_sel_hi:[1,0]
	v_pk_mul_f32 v[128:129], v[128:129], v[150:151] op_sel_hi:[1,0]
	v_pk_mul_f32 v[122:123], v[122:123], v[150:151] op_sel_hi:[1,0]
	v_pk_mul_f32 v[124:125], v[124:125], v[150:151] op_sel_hi:[1,0]
	v_max_f32_e32 v126, 0, v126
	v_max_f32_e32 v127, 0, v127
	v_max_f32_e32 v128, 0, v128
	v_max_f32_e32 v129, 0, v129
	v_max_f32_e32 v122, 0, v122
	v_max_f32_e32 v123, 0, v123
	v_max_f32_e32 v124, 0, v124
	v_max_f32_e32 v125, 0, v125
	v_pk_mul_f32 v[126:127], v[126:127], v[126:127]
	v_pk_mul_f32 v[128:129], v[128:129], v[128:129]
	v_pk_mul_f32 v[122:123], v[122:123], v[122:123]
	v_pk_mul_f32 v[124:125], v[124:125], v[124:125]
	v_cvt_pk_bf16_f32 v126, v126, v127
	v_cvt_pk_bf16_f32 v127, v128, v129
	v_cvt_pk_bf16_f32 v128, v122, v123
	v_cvt_pk_bf16_f32 v129, v124, v125
	global_store_dwordx4 v178, v[126:129], s[40:41]
	v_pk_mul_f32 v[118:119], v[118:119], v[150:151] op_sel_hi:[1,0]
	v_pk_mul_f32 v[120:121], v[120:121], v[150:151] op_sel_hi:[1,0]
	v_pk_mul_f32 v[114:115], v[114:115], v[150:151] op_sel_hi:[1,0]
	v_pk_mul_f32 v[116:117], v[116:117], v[150:151] op_sel_hi:[1,0]
	v_max_f32_e32 v118, 0, v118
	v_max_f32_e32 v119, 0, v119
	v_max_f32_e32 v120, 0, v120
	v_max_f32_e32 v121, 0, v121
	v_max_f32_e32 v114, 0, v114
	v_max_f32_e32 v115, 0, v115
	v_max_f32_e32 v116, 0, v116
	v_max_f32_e32 v117, 0, v117
	v_pk_mul_f32 v[118:119], v[118:119], v[118:119]
	v_pk_mul_f32 v[120:121], v[120:121], v[120:121]
	v_pk_mul_f32 v[114:115], v[114:115], v[114:115]
	v_pk_mul_f32 v[116:117], v[116:117], v[116:117]
	v_cvt_pk_bf16_f32 v118, v118, v119
	v_cvt_pk_bf16_f32 v119, v120, v121
	v_cvt_pk_bf16_f32 v120, v114, v115
	v_cvt_pk_bf16_f32 v121, v116, v117
	global_store_dwordx4 v178, v[118:121], s[40:41] offset:256
	s_add_u32 s40, s22, 0x40000
	s_addc_u32 s41, s23, 0
	v_pk_mul_f32 v[110:111], v[110:111], v[158:159] op_sel_hi:[1,0]
	v_pk_mul_f32 v[112:113], v[112:113], v[158:159] op_sel_hi:[1,0]
	v_pk_mul_f32 v[106:107], v[106:107], v[158:159] op_sel_hi:[1,0]
	v_pk_mul_f32 v[108:109], v[108:109], v[158:159] op_sel_hi:[1,0]
	v_max_f32_e32 v110, 0, v110
	v_max_f32_e32 v111, 0, v111
	v_max_f32_e32 v112, 0, v112
	v_max_f32_e32 v113, 0, v113
	v_max_f32_e32 v106, 0, v106
	v_max_f32_e32 v107, 0, v107
	v_max_f32_e32 v108, 0, v108
	v_max_f32_e32 v109, 0, v109
	v_pk_mul_f32 v[110:111], v[110:111], v[110:111]
	v_pk_mul_f32 v[112:113], v[112:113], v[112:113]
	v_pk_mul_f32 v[106:107], v[106:107], v[106:107]
	v_pk_mul_f32 v[108:109], v[108:109], v[108:109]
	v_cvt_pk_bf16_f32 v110, v110, v111
	v_cvt_pk_bf16_f32 v111, v112, v113
	v_cvt_pk_bf16_f32 v112, v106, v107
	v_cvt_pk_bf16_f32 v113, v108, v109
	global_store_dwordx4 v178, v[110:113], s[40:41]
	v_pk_mul_f32 v[102:103], v[102:103], v[158:159] op_sel_hi:[1,0]
	v_pk_mul_f32 v[104:105], v[104:105], v[158:159] op_sel_hi:[1,0]
	v_pk_mul_f32 v[98:99], v[98:99], v[158:159] op_sel_hi:[1,0]
	v_pk_mul_f32 v[100:101], v[100:101], v[158:159] op_sel_hi:[1,0]
	v_max_f32_e32 v102, 0, v102
	v_max_f32_e32 v103, 0, v103
	v_max_f32_e32 v104, 0, v104
	v_max_f32_e32 v105, 0, v105
	v_max_f32_e32 v98, 0, v98
	v_max_f32_e32 v99, 0, v99
	v_max_f32_e32 v100, 0, v100
	v_max_f32_e32 v101, 0, v101
	v_pk_mul_f32 v[102:103], v[102:103], v[102:103]
	v_pk_mul_f32 v[104:105], v[104:105], v[104:105]
	v_pk_mul_f32 v[98:99], v[98:99], v[98:99]
	v_pk_mul_f32 v[100:101], v[100:101], v[100:101]
	v_cvt_pk_bf16_f32 v102, v102, v103
	v_cvt_pk_bf16_f32 v103, v104, v105
	v_cvt_pk_bf16_f32 v104, v98, v99
	v_cvt_pk_bf16_f32 v105, v100, v101
	global_store_dwordx4 v178, v[102:105], s[40:41] offset:256
	s_add_u32 s40, s22, 0x80000
	s_addc_u32 s41, s23, 0
	v_pk_mul_f32 v[94:95], v[94:95], v[172:173] op_sel_hi:[1,0]
	v_pk_mul_f32 v[96:97], v[96:97], v[172:173] op_sel_hi:[1,0]
	v_pk_mul_f32 v[90:91], v[90:91], v[172:173] op_sel_hi:[1,0]
	v_pk_mul_f32 v[92:93], v[92:93], v[172:173] op_sel_hi:[1,0]
	v_max_f32_e32 v94, 0, v94
	v_max_f32_e32 v95, 0, v95
	v_max_f32_e32 v96, 0, v96
	v_max_f32_e32 v97, 0, v97
	v_max_f32_e32 v90, 0, v90
	v_max_f32_e32 v91, 0, v91
	v_max_f32_e32 v92, 0, v92
	v_max_f32_e32 v93, 0, v93
	v_pk_mul_f32 v[94:95], v[94:95], v[94:95]
	v_pk_mul_f32 v[96:97], v[96:97], v[96:97]
	v_pk_mul_f32 v[90:91], v[90:91], v[90:91]
	v_pk_mul_f32 v[92:93], v[92:93], v[92:93]
	v_cvt_pk_bf16_f32 v94, v94, v95
	v_cvt_pk_bf16_f32 v95, v96, v97
	v_cvt_pk_bf16_f32 v96, v90, v91
	v_cvt_pk_bf16_f32 v97, v92, v93
	global_store_dwordx4 v178, v[94:97], s[40:41]
	v_pk_mul_f32 v[86:87], v[86:87], v[172:173] op_sel_hi:[1,0]
	v_pk_mul_f32 v[88:89], v[88:89], v[172:173] op_sel_hi:[1,0]
	v_pk_mul_f32 v[82:83], v[82:83], v[172:173] op_sel_hi:[1,0]
	v_pk_mul_f32 v[84:85], v[84:85], v[172:173] op_sel_hi:[1,0]
	v_max_f32_e32 v86, 0, v86
	v_max_f32_e32 v87, 0, v87
	v_max_f32_e32 v88, 0, v88
	v_max_f32_e32 v89, 0, v89
	v_max_f32_e32 v82, 0, v82
	v_max_f32_e32 v83, 0, v83
	v_max_f32_e32 v84, 0, v84
	v_max_f32_e32 v85, 0, v85
	v_pk_mul_f32 v[86:87], v[86:87], v[86:87]
	v_pk_mul_f32 v[88:89], v[88:89], v[88:89]
	v_pk_mul_f32 v[82:83], v[82:83], v[82:83]
	v_pk_mul_f32 v[84:85], v[84:85], v[84:85]
	v_cvt_pk_bf16_f32 v86, v86, v87
	v_cvt_pk_bf16_f32 v87, v88, v89
	v_cvt_pk_bf16_f32 v88, v82, v83
	v_cvt_pk_bf16_f32 v89, v84, v85
	global_store_dwordx4 v178, v[86:89], s[40:41] offset:256
	s_add_u32 s40, s22, 0xc0000
	s_addc_u32 s41, s23, 0
	v_pk_mul_f32 v[78:79], v[78:79], v[184:185] op_sel_hi:[1,0]
	v_pk_mul_f32 v[80:81], v[80:81], v[184:185] op_sel_hi:[1,0]
	v_pk_mul_f32 v[74:75], v[74:75], v[184:185] op_sel_hi:[1,0]
	v_pk_mul_f32 v[76:77], v[76:77], v[184:185] op_sel_hi:[1,0]
	v_max_f32_e32 v78, 0, v78
	v_max_f32_e32 v79, 0, v79
	v_max_f32_e32 v80, 0, v80
	v_max_f32_e32 v81, 0, v81
	v_max_f32_e32 v74, 0, v74
	v_max_f32_e32 v75, 0, v75
	v_max_f32_e32 v76, 0, v76
	v_max_f32_e32 v77, 0, v77
	v_pk_mul_f32 v[78:79], v[78:79], v[78:79]
	v_pk_mul_f32 v[80:81], v[80:81], v[80:81]
	v_pk_mul_f32 v[74:75], v[74:75], v[74:75]
	v_pk_mul_f32 v[76:77], v[76:77], v[76:77]
	v_cvt_pk_bf16_f32 v78, v78, v79
	v_cvt_pk_bf16_f32 v79, v80, v81
	v_cvt_pk_bf16_f32 v80, v74, v75
	v_cvt_pk_bf16_f32 v81, v76, v77
	global_store_dwordx4 v178, v[78:81], s[40:41]
	v_pk_mul_f32 v[70:71], v[70:71], v[184:185] op_sel_hi:[1,0]
	v_pk_mul_f32 v[72:73], v[72:73], v[184:185] op_sel_hi:[1,0]
	v_pk_mul_f32 v[66:67], v[66:67], v[184:185] op_sel_hi:[1,0]
	v_pk_mul_f32 v[68:69], v[68:69], v[184:185] op_sel_hi:[1,0]
	v_max_f32_e32 v70, 0, v70
	v_max_f32_e32 v71, 0, v71
	v_max_f32_e32 v72, 0, v72
	v_max_f32_e32 v73, 0, v73
	v_max_f32_e32 v66, 0, v66
	v_max_f32_e32 v67, 0, v67
	v_max_f32_e32 v68, 0, v68
	v_max_f32_e32 v69, 0, v69
	v_pk_mul_f32 v[70:71], v[70:71], v[70:71]
	v_pk_mul_f32 v[72:73], v[72:73], v[72:73]
	v_pk_mul_f32 v[66:67], v[66:67], v[66:67]
	v_pk_mul_f32 v[68:69], v[68:69], v[68:69]
	v_cvt_pk_bf16_f32 v70, v70, v71
	v_cvt_pk_bf16_f32 v71, v72, v73
	v_cvt_pk_bf16_f32 v72, v66, v67
	v_cvt_pk_bf16_f32 v73, v68, v69
	global_store_dwordx4 v178, v[70:73], s[40:41] offset:256
	s_add_u32 s40, s22, 0x200000
	s_addc_u32 s41, s23, 0
	v_pk_mul_f32 v[62:63], v[62:63], v[192:193] op_sel_hi:[1,0]
	v_pk_mul_f32 v[64:65], v[64:65], v[192:193] op_sel_hi:[1,0]
	v_pk_mul_f32 v[58:59], v[58:59], v[192:193] op_sel_hi:[1,0]
	v_pk_mul_f32 v[60:61], v[60:61], v[192:193] op_sel_hi:[1,0]
	v_max_f32_e32 v62, 0, v62
	v_max_f32_e32 v63, 0, v63
	v_max_f32_e32 v64, 0, v64
	v_max_f32_e32 v65, 0, v65
	v_max_f32_e32 v58, 0, v58
	v_max_f32_e32 v59, 0, v59
	v_max_f32_e32 v60, 0, v60
	v_max_f32_e32 v61, 0, v61
	v_pk_mul_f32 v[62:63], v[62:63], v[62:63]
	v_pk_mul_f32 v[64:65], v[64:65], v[64:65]
	v_pk_mul_f32 v[58:59], v[58:59], v[58:59]
	v_pk_mul_f32 v[60:61], v[60:61], v[60:61]
	v_cvt_pk_bf16_f32 v62, v62, v63
	v_cvt_pk_bf16_f32 v63, v64, v65
	v_cvt_pk_bf16_f32 v64, v58, v59
	v_cvt_pk_bf16_f32 v65, v60, v61
	global_store_dwordx4 v178, v[62:65], s[40:41]
	v_pk_mul_f32 v[54:55], v[54:55], v[192:193] op_sel_hi:[1,0]
	v_pk_mul_f32 v[56:57], v[56:57], v[192:193] op_sel_hi:[1,0]
	v_pk_mul_f32 v[50:51], v[50:51], v[192:193] op_sel_hi:[1,0]
	v_pk_mul_f32 v[52:53], v[52:53], v[192:193] op_sel_hi:[1,0]
	v_max_f32_e32 v54, 0, v54
	v_max_f32_e32 v55, 0, v55
	v_max_f32_e32 v56, 0, v56
	v_max_f32_e32 v57, 0, v57
	v_max_f32_e32 v50, 0, v50
	v_max_f32_e32 v51, 0, v51
	v_max_f32_e32 v52, 0, v52
	v_max_f32_e32 v53, 0, v53
	v_pk_mul_f32 v[54:55], v[54:55], v[54:55]
	v_pk_mul_f32 v[56:57], v[56:57], v[56:57]
	v_pk_mul_f32 v[50:51], v[50:51], v[50:51]
	v_pk_mul_f32 v[52:53], v[52:53], v[52:53]
	v_cvt_pk_bf16_f32 v54, v54, v55
	v_cvt_pk_bf16_f32 v55, v56, v57
	v_cvt_pk_bf16_f32 v56, v50, v51
	v_cvt_pk_bf16_f32 v57, v52, v53
	global_store_dwordx4 v178, v[54:57], s[40:41] offset:256
	s_add_u32 s40, s22, 0x240000
	s_addc_u32 s41, s23, 0
	v_pk_mul_f32 v[46:47], v[46:47], v[200:201] op_sel_hi:[1,0]
	v_pk_mul_f32 v[48:49], v[48:49], v[200:201] op_sel_hi:[1,0]
	v_pk_mul_f32 v[42:43], v[42:43], v[200:201] op_sel_hi:[1,0]
	v_pk_mul_f32 v[44:45], v[44:45], v[200:201] op_sel_hi:[1,0]
	v_max_f32_e32 v46, 0, v46
	v_max_f32_e32 v47, 0, v47
	v_max_f32_e32 v48, 0, v48
	v_max_f32_e32 v49, 0, v49
	v_max_f32_e32 v42, 0, v42
	v_max_f32_e32 v43, 0, v43
	v_max_f32_e32 v44, 0, v44
	v_max_f32_e32 v45, 0, v45
	v_pk_mul_f32 v[46:47], v[46:47], v[46:47]
	v_pk_mul_f32 v[48:49], v[48:49], v[48:49]
	v_pk_mul_f32 v[42:43], v[42:43], v[42:43]
	v_pk_mul_f32 v[44:45], v[44:45], v[44:45]
	v_cvt_pk_bf16_f32 v46, v46, v47
	v_cvt_pk_bf16_f32 v47, v48, v49
	v_cvt_pk_bf16_f32 v48, v42, v43
	v_cvt_pk_bf16_f32 v49, v44, v45
	global_store_dwordx4 v178, v[46:49], s[40:41]
	v_pk_mul_f32 v[38:39], v[38:39], v[200:201] op_sel_hi:[1,0]
	v_pk_mul_f32 v[40:41], v[40:41], v[200:201] op_sel_hi:[1,0]
	v_pk_mul_f32 v[34:35], v[34:35], v[200:201] op_sel_hi:[1,0]
	v_pk_mul_f32 v[36:37], v[36:37], v[200:201] op_sel_hi:[1,0]
	v_max_f32_e32 v38, 0, v38
	v_max_f32_e32 v39, 0, v39
	v_max_f32_e32 v40, 0, v40
	v_max_f32_e32 v41, 0, v41
	v_max_f32_e32 v34, 0, v34
	v_max_f32_e32 v35, 0, v35
	v_max_f32_e32 v36, 0, v36
	v_max_f32_e32 v37, 0, v37
	v_pk_mul_f32 v[38:39], v[38:39], v[38:39]
	v_pk_mul_f32 v[40:41], v[40:41], v[40:41]
	v_pk_mul_f32 v[34:35], v[34:35], v[34:35]
	v_pk_mul_f32 v[36:37], v[36:37], v[36:37]
	v_cvt_pk_bf16_f32 v38, v38, v39
	v_cvt_pk_bf16_f32 v39, v40, v41
	v_cvt_pk_bf16_f32 v40, v34, v35
	v_cvt_pk_bf16_f32 v41, v36, v37
	global_store_dwordx4 v178, v[38:41], s[40:41] offset:256
	s_add_u32 s40, s22, 0x280000
	s_addc_u32 s41, s23, 0
	v_pk_mul_f32 v[30:31], v[30:31], v[214:215] op_sel_hi:[1,0]
	v_pk_mul_f32 v[32:33], v[32:33], v[214:215] op_sel_hi:[1,0]
	v_pk_mul_f32 v[26:27], v[26:27], v[214:215] op_sel_hi:[1,0]
	v_pk_mul_f32 v[28:29], v[28:29], v[214:215] op_sel_hi:[1,0]
	v_max_f32_e32 v30, 0, v30
	v_max_f32_e32 v31, 0, v31
	v_max_f32_e32 v32, 0, v32
	v_max_f32_e32 v33, 0, v33
	v_max_f32_e32 v26, 0, v26
	v_max_f32_e32 v27, 0, v27
	v_max_f32_e32 v28, 0, v28
	v_max_f32_e32 v29, 0, v29
	v_pk_mul_f32 v[30:31], v[30:31], v[30:31]
	v_pk_mul_f32 v[32:33], v[32:33], v[32:33]
	v_pk_mul_f32 v[26:27], v[26:27], v[26:27]
	v_pk_mul_f32 v[28:29], v[28:29], v[28:29]
	v_cvt_pk_bf16_f32 v30, v30, v31
	v_cvt_pk_bf16_f32 v31, v32, v33
	v_cvt_pk_bf16_f32 v32, v26, v27
	v_cvt_pk_bf16_f32 v33, v28, v29
	global_store_dwordx4 v178, v[30:33], s[40:41]
	v_pk_mul_f32 v[22:23], v[22:23], v[214:215] op_sel_hi:[1,0]
	v_pk_mul_f32 v[24:25], v[24:25], v[214:215] op_sel_hi:[1,0]
	v_pk_mul_f32 v[18:19], v[18:19], v[214:215] op_sel_hi:[1,0]
	v_pk_mul_f32 v[20:21], v[20:21], v[214:215] op_sel_hi:[1,0]
	v_max_f32_e32 v22, 0, v22
	v_max_f32_e32 v23, 0, v23
	v_max_f32_e32 v24, 0, v24
	v_max_f32_e32 v25, 0, v25
	v_max_f32_e32 v18, 0, v18
	v_max_f32_e32 v19, 0, v19
	v_max_f32_e32 v20, 0, v20
	v_max_f32_e32 v21, 0, v21
	v_pk_mul_f32 v[22:23], v[22:23], v[22:23]
	v_pk_mul_f32 v[24:25], v[24:25], v[24:25]
	v_pk_mul_f32 v[18:19], v[18:19], v[18:19]
	v_pk_mul_f32 v[20:21], v[20:21], v[20:21]
	v_cvt_pk_bf16_f32 v22, v22, v23
	v_cvt_pk_bf16_f32 v23, v24, v25
	v_cvt_pk_bf16_f32 v24, v18, v19
	v_cvt_pk_bf16_f32 v25, v20, v21
	global_store_dwordx4 v178, v[22:25], s[40:41] offset:256
	s_add_u32 s40, s22, 0x2c0000
	s_addc_u32 s41, s23, 0
	v_pk_mul_f32 v[14:15], v[14:15], v[234:235] op_sel_hi:[1,0]
	v_pk_mul_f32 v[16:17], v[16:17], v[234:235] op_sel_hi:[1,0]
	v_pk_mul_f32 v[10:11], v[10:11], v[234:235] op_sel_hi:[1,0]
	v_pk_mul_f32 v[12:13], v[12:13], v[234:235] op_sel_hi:[1,0]
	v_max_f32_e32 v14, 0, v14
	v_max_f32_e32 v15, 0, v15
	v_max_f32_e32 v16, 0, v16
	v_max_f32_e32 v17, 0, v17
	v_max_f32_e32 v10, 0, v10
	v_max_f32_e32 v11, 0, v11
	v_max_f32_e32 v12, 0, v12
	v_max_f32_e32 v13, 0, v13
	v_pk_mul_f32 v[14:15], v[14:15], v[14:15]
	v_pk_mul_f32 v[16:17], v[16:17], v[16:17]
	v_pk_mul_f32 v[10:11], v[10:11], v[10:11]
	v_pk_mul_f32 v[12:13], v[12:13], v[12:13]
	v_cvt_pk_bf16_f32 v14, v14, v15
	v_cvt_pk_bf16_f32 v15, v16, v17
	v_cvt_pk_bf16_f32 v16, v10, v11
	v_cvt_pk_bf16_f32 v17, v12, v13
	global_store_dwordx4 v178, v[14:17], s[40:41]
	v_pk_mul_f32 v[6:7], v[6:7], v[234:235] op_sel_hi:[1,0]
	v_pk_mul_f32 v[8:9], v[8:9], v[234:235] op_sel_hi:[1,0]
	v_pk_mul_f32 v[2:3], v[2:3], v[234:235] op_sel_hi:[1,0]
	v_pk_mul_f32 v[4:5], v[4:5], v[234:235] op_sel_hi:[1,0]
	v_max_f32_e32 v6, 0, v6
	v_max_f32_e32 v7, 0, v7
	v_max_f32_e32 v8, 0, v8
	v_max_f32_e32 v9, 0, v9
	v_max_f32_e32 v2, 0, v2
	v_max_f32_e32 v3, 0, v3
	v_max_f32_e32 v4, 0, v4
	v_max_f32_e32 v5, 0, v5
	v_pk_mul_f32 v[6:7], v[6:7], v[6:7]
	v_pk_mul_f32 v[8:9], v[8:9], v[8:9]
	v_pk_mul_f32 v[2:3], v[2:3], v[2:3]
	v_pk_mul_f32 v[4:5], v[4:5], v[4:5]
	v_cvt_pk_bf16_f32 v6, v6, v7
	v_cvt_pk_bf16_f32 v7, v8, v9
	v_cvt_pk_bf16_f32 v8, v2, v3
	v_cvt_pk_bf16_f32 v9, v4, v5
	global_store_dwordx4 v178, v[6:9], s[40:41] offset:256
	s_mov_b32 s33, 0xf800000
	s_mov_b64 s[40:41], -1
	s_andn2_b64 vcc, exec, s[38:39]
	s_cbranch_vccnz .LBB0_1948
	s_andn2_b64 vcc, exec, s[2:3]
	s_cbranch_vccnz .LBB0_1947
	s_barrier
	s_branch .LBB0_1947
